# scan unit: K/V prefetch four chunks ahead made effective (one counted vmcnt(16) per chunk body, prefetch always issued, per-body vmcnt(1..3) waits dropped)
# baseline (speedup 1.0000x reference)
.LBB0_263:
	s_waitcnt vmcnt(16)
	v_add_u32_e32 v138, s75, v136
	v_add_u32_e32 v0, 0x10000, v138
	ds_write_b128 v137, v[38:41]
	ds_read_b32 v0, v0
	v_cvt_f32_f16_sdwa v3, v34 dst_sel:DWORD dst_unused:UNUSED_PAD src0_sel:WORD_1
	v_cvt_f32_f16_e32 v2, v34
	v_cvt_f32_f16_sdwa v5, v35 dst_sel:DWORD dst_unused:UNUSED_PAD src0_sel:WORD_1
	v_cvt_f32_f16_e32 v4, v35
	v_cvt_f32_f16_sdwa v7, v37 dst_sel:DWORD dst_unused:UNUSED_PAD src0_sel:WORD_1
	s_waitcnt lgkmcnt(0)
	v_pk_mul_f32 v[2:3], v[0:1], v[2:3] op_sel_hi:[0,1]
	v_cvt_pk_f16_f32 v2, v2, v3
	v_pk_mul_f32 v[4:5], v[0:1], v[4:5] op_sel_hi:[0,1]
	v_cvt_pk_f16_f32 v3, v4, v5
	v_cvt_f32_f16_sdwa v5, v36 dst_sel:DWORD dst_unused:UNUSED_PAD src0_sel:WORD_1
	v_cvt_f32_f16_e32 v4, v36
	v_cvt_f32_f16_e32 v6, v37
	s_add_i32 s76, s19, -5
	s_cmp_gt_u32 s76, 13
	v_pk_mul_f32 v[4:5], v[0:1], v[4:5] op_sel_hi:[0,1]
	v_pk_mul_f32 v[6:7], v[0:1], v[6:7] op_sel_hi:[0,1]
	v_cvt_pk_f16_f32 v4, v4, v5
	v_cvt_pk_f16_f32 v5, v6, v7
	ds_write_b128 v137, v[2:5] offset:32768
	s_nop 0
	ds_write_b128 v137, v[50:53] offset:4096
	v_add_u32_e32 v0, 0x10100, v138
	ds_read_b32 v0, v0
	v_cvt_f32_f16_sdwa v3, v42 dst_sel:DWORD dst_unused:UNUSED_PAD src0_sel:WORD_1
	v_cvt_f32_f16_e32 v2, v42
	v_cvt_f32_f16_sdwa v5, v43 dst_sel:DWORD dst_unused:UNUSED_PAD src0_sel:WORD_1
	v_cvt_f32_f16_e32 v4, v43
	v_cvt_f32_f16_sdwa v7, v45 dst_sel:DWORD dst_unused:UNUSED_PAD src0_sel:WORD_1
	s_waitcnt lgkmcnt(0)
	v_pk_mul_f32 v[2:3], v[0:1], v[2:3] op_sel_hi:[0,1]
	v_cvt_pk_f16_f32 v2, v2, v3
	v_pk_mul_f32 v[4:5], v[0:1], v[4:5] op_sel_hi:[0,1]
	v_cvt_pk_f16_f32 v3, v4, v5
	v_cvt_f32_f16_sdwa v5, v44 dst_sel:DWORD dst_unused:UNUSED_PAD src0_sel:WORD_1
	v_cvt_f32_f16_e32 v4, v44
	v_cvt_f32_f16_e32 v6, v45
	v_pk_mul_f32 v[4:5], v[0:1], v[4:5] op_sel_hi:[0,1]
	v_pk_mul_f32 v[6:7], v[0:1], v[6:7] op_sel_hi:[0,1]
	v_cvt_pk_f16_f32 v4, v4, v5
	v_cvt_pk_f16_f32 v5, v6, v7
	ds_write_b128 v137, v[2:5] offset:36864
	s_nop 0
	s_add_i32 s12, s29, 3
	s_add_i32 s13, s19, -3
	s_and_b64 s[6:7], s[0:1], exec
	s_cselect_b32 s6, s13, s12
	s_cmp_gt_u32 s76, 13
	s_cselect_b32 s6, 0, s6
	s_lshl_b32 s6, s6, 7
	s_or_b32 s6, s6, s24
	s_mov_b32 s7, s25
	s_lshl_b64 s[12:13], s[6:7], 9
	s_or_b32 s6, s6, 64
	v_lshl_add_u64 v[2:3], v[102:103], 0, s[12:13]
	s_lshl_b64 s[6:7], s[6:7], 9
	v_lshl_add_u64 v[4:5], v[104:105], 0, s[12:13]
	global_load_dwordx4 v[34:37], v[2:3], off
	global_load_dwordx4 v[38:41], v[4:5], off
	v_lshl_add_u64 v[2:3], v[102:103], 0, s[6:7]
	v_lshl_add_u64 v[4:5], v[104:105], 0, s[6:7]
	global_load_dwordx4 v[42:45], v[2:3], off
	global_load_dwordx4 v[50:53], v[4:5], off

.LBB0_271:
	s_add_i32 s83, s23, s75
	v_lshl_add_u64 v[6:7], s[12:13], 0, v[108:109]
	s_add_i32 s12, s83, 0x12400
	s_waitcnt lgkmcnt(0)
	s_barrier
	v_add_u32_e32 v140, s18, v108
	v_mov_b32_e32 v0, s12
	ds_read_b128 v[2:5], v140
	ds_read_b32 v141, v0
	s_add_i32 s12, s83, 0x12480
	v_mov_b32_e32 v0, s12
	ds_read_b32 v0, v0
	s_waitcnt lgkmcnt(2)
	global_store_dwordx4 v[6:7], v[2:5], off
	s_and_b64 vcc, exec, s[6:7]
	s_waitcnt lgkmcnt(1)
	v_max_f32_e32 v2, v141, v141
	v_max_f32_e32 v3, v111, v111
	v_max_f32_e32 v139, v3, v2
	s_cbranch_vccnz .LBB0_289
	v_add_u32_e32 v142, v128, v129
	v_add_u32_e32 v143, v134, v129
	s_nop 0
	ds_read_b64_tr_b16 v[18:19], v142
	ds_read_b64_tr_b16 v[20:21], v142 offset:256
	ds_read_b64_tr_b16 v[98:99], v143 offset:32768
	ds_read_b64_tr_b16 v[100:101], v143 offset:33024
	ds_read_b64_tr_b16 v[152:153], v142 offset:1024
	ds_read_b64_tr_b16 v[154:155], v142 offset:1280
	ds_read_b64_tr_b16 v[156:157], v143 offset:33792
	ds_read_b64_tr_b16 v[158:159], v143 offset:34048
	ds_read_b64_tr_b16 v[160:161], v142 offset:2048
	ds_read_b64_tr_b16 v[162:163], v142 offset:2304
	ds_read_b64_tr_b16 v[164:165], v143 offset:34816
	ds_read_b64_tr_b16 v[166:167], v143 offset:35072
	s_mov_b32 s41, s40
	s_mov_b32 s42, s40
	s_mov_b32 s43, s40
	s_waitcnt lgkmcnt(8)
	v_mfma_f32_32x32x16_f16 v[18:33], v[18:21], v[98:101], 0
	s_mov_b32 s44, s40
	s_mov_b32 s45, s40
	s_mov_b32 s46, s40
	s_mov_b32 s47, s40
	s_mov_b32 s48, s40
	s_mov_b32 s49, s40
	s_mov_b32 s50, s40
	s_mov_b32 s51, s40
	s_mov_b32 s52, s40
	s_mov_b32 s53, s40
	s_mov_b32 s54, s40
	s_mov_b32 s55, s40
	v_mov_b64_e32 v[2:3], s[40:41]
	v_mov_b64_e32 v[4:5], s[42:43]
	v_mov_b64_e32 v[6:7], s[44:45]
	v_mov_b64_e32 v[8:9], s[46:47]
	v_mov_b64_e32 v[10:11], s[48:49]
	v_mov_b64_e32 v[12:13], s[50:51]
	v_mov_b64_e32 v[14:15], s[52:53]
	v_mov_b64_e32 v[16:17], s[54:55]
	s_and_b64 vcc, exec, s[4:5]
	s_cbranch_vccnz .LBB0_274
	v_mov_b32_e32 v131, v130
	v_mov_b32_e32 v132, v130
	v_mov_b32_e32 v133, v130
	s_nop 1
	v_mfma_f32_32x32x16_f16 v[2:17], v[130:133], v[98:101], 0

.LBB0_289:
	s_waitcnt vmcnt(16)
	v_add_u32_e32 v2, 0x10200, v138
	ds_write_b128 v137, v[54:57] offset:16384
	ds_read_b32 v6, v2
	v_cvt_f32_f16_sdwa v3, v46 dst_sel:DWORD dst_unused:UNUSED_PAD src0_sel:WORD_1
	v_cvt_f32_f16_e32 v2, v46
	v_cvt_f32_f16_sdwa v5, v47 dst_sel:DWORD dst_unused:UNUSED_PAD src0_sel:WORD_1
	v_cvt_f32_f16_e32 v4, v47
	s_nop 0
	v_cvt_f32_f16_sdwa v9, v49 dst_sel:DWORD dst_unused:UNUSED_PAD src0_sel:WORD_1
	s_waitcnt lgkmcnt(0)
	v_pk_mul_f32 v[2:3], v[6:7], v[2:3] op_sel_hi:[0,1]
	v_cvt_pk_f16_f32 v2, v2, v3
	v_pk_mul_f32 v[4:5], v[6:7], v[4:5] op_sel_hi:[0,1]
	v_cvt_pk_f16_f32 v3, v4, v5
	v_cvt_f32_f16_sdwa v5, v48 dst_sel:DWORD dst_unused:UNUSED_PAD src0_sel:WORD_1
	v_cvt_f32_f16_e32 v4, v48
	v_cvt_f32_f16_e32 v8, v49
	s_cmp_gt_u32 s76, 12
	v_pk_mul_f32 v[4:5], v[6:7], v[4:5] op_sel_hi:[0,1]
	v_pk_mul_f32 v[6:7], v[6:7], v[8:9] op_sel_hi:[0,1]
	v_cvt_pk_f16_f32 v4, v4, v5
	v_cvt_pk_f16_f32 v5, v6, v7
	ds_write_b128 v137, v[2:5] offset:49152
	s_nop 0
	ds_write_b128 v137, v[62:65] offset:20480
	v_add_u32_e32 v2, 0x10300, v138
	ds_read_b32 v6, v2
	v_cvt_f32_f16_sdwa v3, v58 dst_sel:DWORD dst_unused:UNUSED_PAD src0_sel:WORD_1
	v_cvt_f32_f16_e32 v2, v58
	v_cvt_f32_f16_sdwa v5, v59 dst_sel:DWORD dst_unused:UNUSED_PAD src0_sel:WORD_1
	v_cvt_f32_f16_e32 v4, v59
	v_cvt_f32_f16_sdwa v9, v61 dst_sel:DWORD dst_unused:UNUSED_PAD src0_sel:WORD_1
	s_waitcnt lgkmcnt(0)
	v_pk_mul_f32 v[2:3], v[6:7], v[2:3] op_sel_hi:[0,1]
	v_cvt_pk_f16_f32 v2, v2, v3
	v_pk_mul_f32 v[4:5], v[6:7], v[4:5] op_sel_hi:[0,1]
	v_cvt_pk_f16_f32 v3, v4, v5
	v_cvt_f32_f16_sdwa v5, v60 dst_sel:DWORD dst_unused:UNUSED_PAD src0_sel:WORD_1
	v_cvt_f32_f16_e32 v4, v60
	v_cvt_f32_f16_e32 v8, v61
	v_pk_mul_f32 v[4:5], v[6:7], v[4:5] op_sel_hi:[0,1]
	v_pk_mul_f32 v[6:7], v[6:7], v[8:9] op_sel_hi:[0,1]
	v_cvt_pk_f16_f32 v4, v4, v5
	v_cvt_pk_f16_f32 v5, v6, v7
	ds_write_b128 v137, v[2:5] offset:53248
	s_nop 0
	s_add_i32 s14, s29, 2
	s_add_i32 s15, s19, -2
	s_and_b64 s[12:13], s[0:1], exec
	s_cselect_b32 s12, s15, s14
	s_cmp_gt_u32 s76, 12
	s_cselect_b32 s12, 0, s12
	s_lshl_b32 s12, s12, 7
	s_or_b32 s12, s12, s24
	s_mov_b32 s13, s25
	s_lshl_b64 s[14:15], s[12:13], 9
	s_or_b32 s12, s12, 64
	v_lshl_add_u64 v[2:3], v[102:103], 0, s[14:15]
	s_lshl_b64 s[12:13], s[12:13], 9
	v_lshl_add_u64 v[4:5], v[104:105], 0, s[14:15]
	global_load_dwordx4 v[46:49], v[2:3], off
	global_load_dwordx4 v[54:57], v[4:5], off
	v_lshl_add_u64 v[2:3], v[102:103], 0, s[12:13]
	v_lshl_add_u64 v[4:5], v[104:105], 0, s[12:13]
	global_load_dwordx4 v[58:61], v[2:3], off
	global_load_dwordx4 v[62:65], v[4:5], off

.LBB0_300:
	v_add_u32_e32 v143, v128, v129
	v_add_u32_e32 v144, v134, v129
	ds_read_b64_tr_b16 v[18:19], v143 offset:16384
	ds_read_b64_tr_b16 v[20:21], v143 offset:16640
	ds_read_b64_tr_b16 v[98:99], v144 offset:49152
	ds_read_b64_tr_b16 v[100:101], v144 offset:49408
	ds_read_b64_tr_b16 v[152:153], v143 offset:17408
	ds_read_b64_tr_b16 v[154:155], v143 offset:17664
	ds_read_b64_tr_b16 v[156:157], v144 offset:50176
	ds_read_b64_tr_b16 v[158:159], v144 offset:50432
	ds_read_b64_tr_b16 v[160:161], v143 offset:18432
	ds_read_b64_tr_b16 v[162:163], v143 offset:18688
	ds_read_b64_tr_b16 v[164:165], v144 offset:51200
	ds_read_b64_tr_b16 v[166:167], v144 offset:51456
	s_mov_b32 s41, s40
	s_mov_b32 s42, s40
	s_mov_b32 s43, s40
	s_waitcnt lgkmcnt(8)
	v_mfma_f32_32x32x16_f16 v[18:33], v[18:21], v[98:101], 0
	s_mov_b32 s44, s40
	s_mov_b32 s45, s40
	s_mov_b32 s46, s40
	s_mov_b32 s47, s40
	s_mov_b32 s48, s40
	s_mov_b32 s49, s40
	s_mov_b32 s50, s40
	s_mov_b32 s51, s40
	s_mov_b32 s52, s40
	s_mov_b32 s53, s40
	s_mov_b32 s54, s40
	s_mov_b32 s55, s40
	v_mov_b64_e32 v[2:3], s[40:41]
	v_mov_b64_e32 v[4:5], s[42:43]
	v_mov_b64_e32 v[6:7], s[44:45]
	v_mov_b64_e32 v[8:9], s[46:47]
	v_mov_b64_e32 v[10:11], s[48:49]
	v_mov_b64_e32 v[12:13], s[50:51]
	v_mov_b64_e32 v[14:15], s[52:53]
	v_mov_b64_e32 v[16:17], s[54:55]
	s_and_b64 vcc, exec, s[4:5]
	s_cbranch_vccnz .LBB0_302
	v_mov_b32_e32 v131, v130
	v_mov_b32_e32 v132, v130
	v_mov_b32_e32 v133, v130
	s_nop 1
	v_mfma_f32_32x32x16_f16 v[2:17], v[130:133], v[98:101], 0

.LBB0_317:
	s_waitcnt vmcnt(16)
	v_add_u32_e32 v0, 0x10400, v138
	ds_write_b128 v137, v[70:73]
	ds_read_b32 v0, v0
	v_cvt_f32_f16_sdwa v3, v66 dst_sel:DWORD dst_unused:UNUSED_PAD src0_sel:WORD_1
	v_cvt_f32_f16_e32 v2, v66
	v_cvt_f32_f16_sdwa v5, v67 dst_sel:DWORD dst_unused:UNUSED_PAD src0_sel:WORD_1
	v_cvt_f32_f16_e32 v4, v67
	v_cvt_f32_f16_sdwa v7, v69 dst_sel:DWORD dst_unused:UNUSED_PAD src0_sel:WORD_1
	s_waitcnt lgkmcnt(0)
	v_pk_mul_f32 v[2:3], v[0:1], v[2:3] op_sel_hi:[0,1]
	v_cvt_pk_f16_f32 v2, v2, v3
	v_pk_mul_f32 v[4:5], v[0:1], v[4:5] op_sel_hi:[0,1]
	v_cvt_pk_f16_f32 v3, v4, v5
	v_cvt_f32_f16_sdwa v5, v68 dst_sel:DWORD dst_unused:UNUSED_PAD src0_sel:WORD_1
	v_cvt_f32_f16_e32 v4, v68
	v_cvt_f32_f16_e32 v6, v69
	s_cmp_gt_u32 s76, 11
	v_pk_mul_f32 v[4:5], v[0:1], v[4:5] op_sel_hi:[0,1]
	v_pk_mul_f32 v[6:7], v[0:1], v[6:7] op_sel_hi:[0,1]
	v_cvt_pk_f16_f32 v4, v4, v5
	v_cvt_pk_f16_f32 v5, v6, v7
	ds_write_b128 v137, v[2:5] offset:32768
	ds_write_b128 v137, v[78:81] offset:4096
	v_add_u32_e32 v0, 0x10500, v138
	ds_read_b32 v0, v0
	v_cvt_f32_f16_sdwa v3, v74 dst_sel:DWORD dst_unused:UNUSED_PAD src0_sel:WORD_1
	v_cvt_f32_f16_e32 v2, v74
	v_cvt_f32_f16_sdwa v5, v75 dst_sel:DWORD dst_unused:UNUSED_PAD src0_sel:WORD_1
	v_cvt_f32_f16_e32 v4, v75
	v_cvt_f32_f16_sdwa v7, v77 dst_sel:DWORD dst_unused:UNUSED_PAD src0_sel:WORD_1
	s_waitcnt lgkmcnt(0)
	v_pk_mul_f32 v[2:3], v[0:1], v[2:3] op_sel_hi:[0,1]
	v_cvt_pk_f16_f32 v2, v2, v3
	v_pk_mul_f32 v[4:5], v[0:1], v[4:5] op_sel_hi:[0,1]
	v_cvt_pk_f16_f32 v3, v4, v5
	v_cvt_f32_f16_sdwa v5, v76 dst_sel:DWORD dst_unused:UNUSED_PAD src0_sel:WORD_1
	v_cvt_f32_f16_e32 v4, v76
	v_cvt_f32_f16_e32 v6, v77
	v_pk_mul_f32 v[4:5], v[0:1], v[4:5] op_sel_hi:[0,1]
	v_pk_mul_f32 v[6:7], v[0:1], v[6:7] op_sel_hi:[0,1]
	v_cvt_pk_f16_f32 v4, v4, v5
	v_cvt_pk_f16_f32 v5, v6, v7
	ds_write_b128 v137, v[2:5] offset:36864
	s_nop 0
	s_add_i32 s14, s29, 1
	s_add_i32 s15, s19, -1
	s_and_b64 s[12:13], s[0:1], exec
	s_cselect_b32 s12, s15, s14
	s_cmp_gt_u32 s76, 11
	s_cselect_b32 s12, 0, s12
	s_lshl_b32 s12, s12, 7
	s_add_u32 s12, s24, s12
	s_addc_u32 s13, s25, 0
	s_lshl_b64 s[12:13], s[12:13], 9
	v_lshl_add_u64 v[2:3], v[102:103], 0, s[12:13]
	v_lshl_add_u64 v[4:5], v[104:105], 0, s[12:13]
	s_bitset1_b32 s12, 15
	global_load_dwordx4 v[66:69], v[2:3], off
	global_load_dwordx4 v[70:73], v[4:5], off
	v_lshl_add_u64 v[2:3], v[102:103], 0, s[12:13]
	v_lshl_add_u64 v[4:5], v[104:105], 0, s[12:13]
	global_load_dwordx4 v[74:77], v[2:3], off
	global_load_dwordx4 v[78:81], v[4:5], off

.LBB0_325:
	v_lshl_add_u64 v[6:7], s[12:13], 0, v[108:109]
	s_add_i32 s12, s83, 0x12408
	s_waitcnt lgkmcnt(0)
	s_barrier
	v_mov_b32_e32 v0, s12
	ds_read_b128 v[2:5], v140
	ds_read_b32 v141, v0
	s_add_i32 s12, s83, 0x12488
	v_mov_b32_e32 v0, s12
	ds_read_b32 v0, v0
	s_waitcnt lgkmcnt(2)
	global_store_dwordx4 v[6:7], v[2:5], off
	s_and_b64 vcc, exec, s[6:7]
	s_waitcnt lgkmcnt(1)
	v_max_f32_e32 v2, v141, v141
	v_max_f32_e32 v3, v111, v111
	v_max_f32_e32 v140, v3, v2
	s_cbranch_vccnz .LBB0_343
	v_add_u32_e32 v142, v128, v129
	v_add_u32_e32 v143, v134, v129
	ds_read_b64_tr_b16 v[18:19], v142
	ds_read_b64_tr_b16 v[20:21], v142 offset:256
	ds_read_b64_tr_b16 v[98:99], v143 offset:32768
	ds_read_b64_tr_b16 v[100:101], v143 offset:33024
	ds_read_b64_tr_b16 v[152:153], v142 offset:1024
	ds_read_b64_tr_b16 v[154:155], v142 offset:1280
	ds_read_b64_tr_b16 v[156:157], v143 offset:33792
	ds_read_b64_tr_b16 v[158:159], v143 offset:34048
	ds_read_b64_tr_b16 v[160:161], v142 offset:2048
	ds_read_b64_tr_b16 v[162:163], v142 offset:2304
	ds_read_b64_tr_b16 v[164:165], v143 offset:34816
	ds_read_b64_tr_b16 v[166:167], v143 offset:35072
	s_mov_b32 s41, s40
	s_mov_b32 s42, s40
	s_mov_b32 s43, s40
	s_waitcnt lgkmcnt(8)
	v_mfma_f32_32x32x16_f16 v[18:33], v[18:21], v[98:101], 0
	s_mov_b32 s44, s40
	s_mov_b32 s45, s40
	s_mov_b32 s46, s40
	s_mov_b32 s47, s40
	s_mov_b32 s48, s40
	s_mov_b32 s49, s40
	s_mov_b32 s50, s40
	s_mov_b32 s51, s40
	s_mov_b32 s52, s40
	s_mov_b32 s53, s40
	s_mov_b32 s54, s40
	s_mov_b32 s55, s40
	v_mov_b64_e32 v[2:3], s[40:41]
	v_mov_b64_e32 v[4:5], s[42:43]
	v_mov_b64_e32 v[6:7], s[44:45]
	v_mov_b64_e32 v[8:9], s[46:47]
	v_mov_b64_e32 v[10:11], s[48:49]
	v_mov_b64_e32 v[12:13], s[50:51]
	v_mov_b64_e32 v[14:15], s[52:53]
	v_mov_b64_e32 v[16:17], s[54:55]
	s_and_b64 vcc, exec, s[4:5]
	s_cbranch_vccnz .LBB0_328
	v_mov_b32_e32 v131, v130
	v_mov_b32_e32 v132, v130
	v_mov_b32_e32 v133, v130
	s_nop 1
	v_mfma_f32_32x32x16_f16 v[2:17], v[130:133], v[98:101], 0

.LBB0_344:
	s_waitcnt vmcnt(16)
	v_add_u32_e32 v0, 0x10600, v138
	ds_write_b128 v137, v[86:89] offset:16384
	ds_read_b32 v0, v0
	v_cvt_f32_f16_sdwa v3, v82 dst_sel:DWORD dst_unused:UNUSED_PAD src0_sel:WORD_1
	v_cvt_f32_f16_e32 v2, v82
	v_cvt_f32_f16_sdwa v5, v83 dst_sel:DWORD dst_unused:UNUSED_PAD src0_sel:WORD_1
	v_cvt_f32_f16_e32 v4, v83
	v_cvt_f32_f16_sdwa v7, v85 dst_sel:DWORD dst_unused:UNUSED_PAD src0_sel:WORD_1
	s_waitcnt lgkmcnt(0)
	v_pk_mul_f32 v[2:3], v[0:1], v[2:3] op_sel_hi:[0,1]
	v_cvt_pk_f16_f32 v2, v2, v3
	v_pk_mul_f32 v[4:5], v[0:1], v[4:5] op_sel_hi:[0,1]
	v_cvt_pk_f16_f32 v3, v4, v5
	v_cvt_f32_f16_sdwa v5, v84 dst_sel:DWORD dst_unused:UNUSED_PAD src0_sel:WORD_1
	v_cvt_f32_f16_e32 v4, v84
	v_cvt_f32_f16_e32 v6, v85
	s_cmp_gt_u32 s76, 10
	v_pk_mul_f32 v[4:5], v[0:1], v[4:5] op_sel_hi:[0,1]
	v_pk_mul_f32 v[6:7], v[0:1], v[6:7] op_sel_hi:[0,1]
	v_cvt_pk_f16_f32 v4, v4, v5
	v_cvt_pk_f16_f32 v5, v6, v7
	ds_write_b128 v137, v[2:5] offset:49152
	s_nop 0
	ds_write_b128 v137, v[94:97] offset:20480
	v_add_u32_e32 v0, 0x10700, v138
	ds_read_b32 v0, v0
	v_cvt_f32_f16_sdwa v3, v90 dst_sel:DWORD dst_unused:UNUSED_PAD src0_sel:WORD_1
	v_cvt_f32_f16_e32 v2, v90
	v_cvt_f32_f16_sdwa v5, v91 dst_sel:DWORD dst_unused:UNUSED_PAD src0_sel:WORD_1
	v_cvt_f32_f16_e32 v4, v91
	v_cvt_f32_f16_sdwa v7, v93 dst_sel:DWORD dst_unused:UNUSED_PAD src0_sel:WORD_1
	s_waitcnt lgkmcnt(0)
	v_pk_mul_f32 v[2:3], v[0:1], v[2:3] op_sel_hi:[0,1]
	v_cvt_pk_f16_f32 v2, v2, v3
	v_pk_mul_f32 v[4:5], v[0:1], v[4:5] op_sel_hi:[0,1]
	v_cvt_pk_f16_f32 v3, v4, v5
	v_cvt_f32_f16_sdwa v5, v92 dst_sel:DWORD dst_unused:UNUSED_PAD src0_sel:WORD_1
	v_cvt_f32_f16_e32 v4, v92
	v_cvt_f32_f16_e32 v6, v93
	v_pk_mul_f32 v[4:5], v[0:1], v[4:5] op_sel_hi:[0,1]
	v_pk_mul_f32 v[6:7], v[0:1], v[6:7] op_sel_hi:[0,1]
	v_cvt_pk_f16_f32 v4, v4, v5
	v_cvt_pk_f16_f32 v5, v6, v7
	ds_write_b128 v137, v[2:5] offset:53248
	s_nop 0
	s_and_b64 s[12:13], s[0:1], exec
	s_cselect_b32 s12, s19, s29
	s_cmp_gt_u32 s76, 10
	s_cselect_b32 s12, 0, s12
	s_lshl_b32 s12, s12, 7
	s_add_u32 s12, s24, s12
	s_addc_u32 s13, s25, 0
	s_lshl_b64 s[12:13], s[12:13], 9
	v_lshl_add_u64 v[2:3], v[102:103], 0, s[12:13]
	v_lshl_add_u64 v[4:5], v[104:105], 0, s[12:13]
	s_bitset1_b32 s12, 15
	global_load_dwordx4 v[82:85], v[2:3], off
	global_load_dwordx4 v[86:89], v[4:5], off
	v_lshl_add_u64 v[2:3], v[102:103], 0, s[12:13]
	v_lshl_add_u64 v[4:5], v[104:105], 0, s[12:13]
	global_load_dwordx4 v[90:93], v[2:3], off
	global_load_dwordx4 v[94:97], v[4:5], off
